# top-k threshold search: the four ballot compares of an iteration issue back to back into separate SGPR pairs before the popcounts (no VALU->SALU round trip per compare)
# speedup vs baseline: 1.0030x; 1.0030x over previous
.LBB0_3853:
	s_lshl_b64 vcc, 1, s28
	s_or_b64 s[26:27], vcc, s[88:89]
	v_cmp_le_u64_e64 s[56:57], s[26:27], v[18:19]
	v_cmp_le_u64_e64 s[92:93], s[26:27], v[16:17]
	v_cmp_le_u64_e64 s[98:99], s[26:27], v[14:15]
	v_cmp_le_u64_e32 vcc, s[26:27], v[12:13]
	s_bcnt1_i32_b64 s51, s[56:57]
	s_bcnt1_i32_b64 s53, s[92:93]
	s_add_i32 s51, s51, s53
	s_bcnt1_i32_b64 s53, s[98:99]
	s_add_i32 s51, s51, s53
	s_bcnt1_i32_b64 s53, vcc
	s_add_i32 s51, s51, s53
	s_cmp_gt_u32 s51, 15
	s_cselect_b32 s89, s27, s89
	s_cselect_b32 s88, s26, s88
	s_cmp_lg_u32 s51, 16
	s_cselect_b64 s[26:27], -1, 0
	s_cmp_lg_u32 s28, 0
	s_cselect_b64 vcc, -1, 0
	s_and_b64 s[26:27], s[26:27], vcc
	s_add_u32 s28, s28, -1
	s_addc_u32 s29, s29, -1
	s_and_b64 vcc, exec, s[26:27]
	s_cbranch_vccnz .LBB0_3853
	v_lshlrev_b64 v[2:3], v175, -1
	v_not_b32_e32 v2, v2
	v_cmp_le_u64_e32 vcc, s[88:89], v[18:19]
	v_not_b32_e32 v1, v3
	v_mov_b32_e32 v19, v0
	v_and_b32_e32 v11, vcc_lo, v2
	v_and_b32_e32 v3, vcc_hi, v1
	v_bcnt_u32_b32 v11, v11, 0
	v_bcnt_u32_b32 v18, v3, v11
	v_cmp_gt_u64_e64 s[28:29], 16, v[18:19]
	s_and_b64 s[26:27], vcc, s[28:29]
	v_cndmask_b32_e64 v3, v175, -1, s[12:13]
	s_and_saveexec_b64 s[28:29], s[26:27]
	v_lshl_add_u32 v11, v18, 2, s5
	ds_write_b32 v11, v3
	s_or_b64 exec, exec, s[28:29]
	s_bcnt1_i32_b64 s51, vcc
	v_cmp_le_u64_e32 vcc, s[88:89], v[16:17]
	s_nop 1
	v_and_b32_e32 v16, vcc_lo, v2
	v_and_b32_e32 v11, vcc_hi, v1
	v_bcnt_u32_b32 v16, v16, 0
	v_bcnt_u32_b32 v11, v11, v16
	v_add_u32_e32 v16, s51, v11
	v_cmp_gt_u32_e64 s[28:29], 16, v16
	s_and_b64 s[26:27], vcc, s[28:29]
	v_cndmask_b32_e64 v11, v9, -1, s[14:15]
	s_and_saveexec_b64 s[28:29], s[26:27]
	v_lshl_add_u32 v9, v16, 2, s5
	ds_write_b32 v9, v11
	s_or_b64 exec, exec, s[28:29]
	s_bcnt1_i32_b64 s26, vcc
	v_cmp_le_u64_e32 vcc, s[88:89], v[14:15]
	s_add_i32 s51, s26, s51
	v_cndmask_b32_e64 v20, v7, -1, s[20:21]
	v_and_b32_e32 v14, vcc_lo, v2
	v_and_b32_e32 v9, vcc_hi, v1
	v_bcnt_u32_b32 v14, v14, 0
	v_bcnt_u32_b32 v9, v9, v14
	v_add_u32_e32 v9, s51, v9
	v_cmp_gt_u32_e64 s[28:29], 16, v9
	s_and_b64 s[26:27], vcc, s[28:29]
	s_and_saveexec_b64 s[28:29], s[26:27]
	v_lshl_add_u32 v7, v9, 2, s5
	ds_write_b32 v7, v20
	s_or_b64 exec, exec, s[28:29]
	s_bcnt1_i32_b64 s26, vcc
	v_cmp_le_u64_e32 vcc, s[88:89], v[12:13]
	s_add_i32 s51, s51, s26
	v_cndmask_b32_e64 v21, v5, -1, s[24:25]
	v_and_b32_e32 v9, vcc_lo, v2
	v_and_b32_e32 v7, vcc_hi, v1
	v_bcnt_u32_b32 v9, v9, 0
	v_bcnt_u32_b32 v7, v7, v9
	v_add_u32_e32 v7, s51, v7
	v_cmp_gt_u32_e64 s[28:29], 16, v7
	s_and_b64 s[26:27], vcc, s[28:29]
	s_and_saveexec_b64 s[28:29], s[26:27]
	v_lshl_add_u32 v5, v7, 2, s5
	ds_write_b32 v5, v21
	s_or_b64 exec, exec, s[28:29]
	v_lshl_add_u32 v5, v175, 2, s4
	ds_read2st64_b32 v[12:13], v5 offset1:1
	ds_read2st64_b32 v[22:23], v5 offset0:2 offset1:3
	v_mov_b32_e32 v15, v0
	s_mov_b64 s[88:89], 0
	s_mov_b64 s[28:29], 39
	s_waitcnt lgkmcnt(1)
	v_cndmask_b32_e64 v5, v12, v173, s[10:11]
	v_cndmask_b32_e64 v5, v5, v170, s[12:13]
	v_cndmask_b32_e64 v7, v13, v173, s[16:17]
	v_not_b32_e32 v9, v5
	v_cmp_gt_i32_e32 vcc, 0, v5
	v_mov_b32_e32 v13, v0
	s_nop 0
	v_cndmask_b32_e64 v14, -|v5|, v9, vcc
	v_cndmask_b32_e64 v5, v7, v170, s[14:15]
	v_not_b32_e32 v7, v5
	v_cmp_gt_i32_e32 vcc, 0, v5
	v_lshlrev_b64 v[18:19], 8, v[14:15]
	v_or_b32_e32 v18, v18, v4
	v_cndmask_b32_e64 v12, -|v5|, v7, vcc
	s_waitcnt lgkmcnt(0)
	v_cndmask_b32_e64 v5, v22, v173, s[18:19]
	v_cndmask_b32_e64 v5, v5, v170, s[20:21]
	v_not_b32_e32 v7, v5
	v_cmp_gt_i32_e32 vcc, 0, v5
	v_lshlrev_b64 v[16:17], 8, v[12:13]
	v_or_b32_e32 v16, v16, v6
	v_cndmask_b32_e64 v12, -|v5|, v7, vcc
	v_cndmask_b32_e64 v5, v23, v173, s[22:23]
	v_cndmask_b32_e64 v5, v5, v170, s[24:25]
	v_not_b32_e32 v7, v5
	v_cmp_gt_i32_e32 vcc, 0, v5
	v_lshlrev_b64 v[14:15], 8, v[12:13]
	v_or_b32_e32 v14, v14, v8
	v_cndmask_b32_e64 v12, -|v5|, v7, vcc
	v_lshlrev_b64 v[12:13], 8, v[12:13]
	v_or_b32_e32 v12, v12, v10
.LBB0_3863:
	s_lshl_b64 s[26:27], 1, s28
	s_or_b64 s[26:27], s[26:27], s[88:89]
	v_cmp_le_u64_e64 s[56:57], s[26:27], v[18:19]
	v_cmp_le_u64_e64 s[92:93], s[26:27], v[16:17]
	v_cmp_le_u64_e64 s[98:99], s[26:27], v[14:15]
	v_cmp_le_u64_e32 vcc, s[26:27], v[12:13]
	s_bcnt1_i32_b64 s51, s[56:57]
	s_bcnt1_i32_b64 s53, s[92:93]
	s_add_i32 s51, s51, s53
	s_bcnt1_i32_b64 s53, s[98:99]
	s_add_i32 s51, s51, s53
	s_bcnt1_i32_b64 s53, vcc
	s_add_i32 s51, s51, s53
	s_cmp_gt_u32 s51, 15
	s_cselect_b32 s89, s27, s89
	s_cselect_b32 s88, s26, s88
	s_cmp_lg_u32 s51, 16
	s_cselect_b64 s[26:27], -1, 0
	s_cmp_lg_u32 s28, 0
	s_cselect_b64 vcc, -1, 0
	s_and_b64 s[26:27], s[26:27], vcc
	s_add_u32 s28, s28, -1
	s_addc_u32 s29, s29, -1
	s_and_b64 vcc, exec, s[26:27]
	s_cbranch_vccnz .LBB0_3863
	v_cmp_le_u64_e32 vcc, s[88:89], v[18:19]
	v_mov_b32_e32 v19, v0
	s_nop 0
	v_and_b32_e32 v7, vcc_lo, v2
	v_and_b32_e32 v5, vcc_hi, v1
	v_bcnt_u32_b32 v7, v7, 0
	v_bcnt_u32_b32 v18, v5, v7
	v_cmp_gt_u64_e64 s[28:29], 16, v[18:19]
	s_and_b64 s[26:27], vcc, s[28:29]
	s_and_saveexec_b64 s[28:29], s[26:27]
	v_lshl_add_u32 v5, v18, 2, s1
	ds_write_b32 v5, v3
	s_or_b64 exec, exec, s[28:29]
	s_bcnt1_i32_b64 s51, vcc
	v_cmp_le_u64_e32 vcc, s[88:89], v[16:17]
	s_nop 1
	v_and_b32_e32 v7, vcc_lo, v2
	v_and_b32_e32 v5, vcc_hi, v1
	v_bcnt_u32_b32 v7, v7, 0
	v_bcnt_u32_b32 v5, v5, v7
	v_add_u32_e32 v5, s51, v5
	v_cmp_gt_u32_e64 s[28:29], 16, v5
	s_and_b64 s[26:27], vcc, s[28:29]
	s_and_saveexec_b64 s[28:29], s[26:27]
	v_lshl_add_u32 v5, v5, 2, s1
	ds_write_b32 v5, v11
	s_or_b64 exec, exec, s[28:29]
	s_bcnt1_i32_b64 s26, vcc
	v_cmp_le_u64_e32 vcc, s[88:89], v[14:15]
	s_add_i32 s51, s26, s51
	s_nop 0
	v_and_b32_e32 v7, vcc_lo, v2
	v_and_b32_e32 v5, vcc_hi, v1
	v_bcnt_u32_b32 v7, v7, 0
	v_bcnt_u32_b32 v5, v5, v7
	v_add_u32_e32 v5, s51, v5
	v_cmp_gt_u32_e64 s[28:29], 16, v5
	s_and_b64 s[26:27], vcc, s[28:29]
	s_and_saveexec_b64 s[28:29], s[26:27]
	v_lshl_add_u32 v5, v5, 2, s1
	ds_write_b32 v5, v20
	s_or_b64 exec, exec, s[28:29]
	s_bcnt1_i32_b64 s26, vcc
	v_cmp_le_u64_e32 vcc, s[88:89], v[12:13]
	s_add_i32 s51, s51, s26
	s_nop 0
	v_and_b32_e32 v7, vcc_lo, v2
	v_and_b32_e32 v5, vcc_hi, v1
	v_bcnt_u32_b32 v7, v7, 0
	v_bcnt_u32_b32 v5, v5, v7
	v_add_u32_e32 v5, s51, v5
	v_cmp_gt_u32_e64 s[28:29], 16, v5
	s_and_b64 s[26:27], vcc, s[28:29]
	s_and_saveexec_b64 s[28:29], s[26:27]
	v_lshl_add_u32 v5, v5, 2, s1
	ds_write_b32 v5, v21
	s_or_b64 exec, exec, s[28:29]
	v_lshl_add_u32 v5, v175, 2, s0
	ds_read2st64_b32 v[12:13], v5 offset1:1
	ds_read2st64_b32 v[22:23], v5 offset0:2 offset1:3
	v_mov_b32_e32 v15, v0
	s_mov_b64 s[88:89], 0
	s_mov_b64 s[28:29], 39
	s_waitcnt lgkmcnt(1)
	v_cndmask_b32_e64 v5, v12, v173, s[10:11]
	v_cndmask_b32_e64 v5, v5, v170, s[12:13]
	v_cndmask_b32_e64 v7, v13, v173, s[16:17]
	v_not_b32_e32 v9, v5
	v_cmp_gt_i32_e32 vcc, 0, v5
	v_mov_b32_e32 v13, v0
	s_nop 0
	v_cndmask_b32_e64 v14, -|v5|, v9, vcc
	v_cndmask_b32_e64 v5, v7, v170, s[14:15]
	v_not_b32_e32 v7, v5
	v_cmp_gt_i32_e32 vcc, 0, v5
	v_lshlrev_b64 v[18:19], 8, v[14:15]
	v_or_b32_e32 v18, v18, v4
	v_cndmask_b32_e64 v12, -|v5|, v7, vcc
	s_waitcnt lgkmcnt(0)
	v_cndmask_b32_e64 v5, v22, v173, s[18:19]
	v_cndmask_b32_e64 v5, v5, v170, s[20:21]
	v_not_b32_e32 v7, v5
	v_cmp_gt_i32_e32 vcc, 0, v5
	v_lshlrev_b64 v[16:17], 8, v[12:13]
	v_or_b32_e32 v16, v16, v6
	v_cndmask_b32_e64 v12, -|v5|, v7, vcc
	v_cndmask_b32_e64 v5, v23, v173, s[22:23]
	v_cndmask_b32_e64 v5, v5, v170, s[24:25]
	v_not_b32_e32 v7, v5
	v_cmp_gt_i32_e32 vcc, 0, v5
	v_lshlrev_b64 v[14:15], 8, v[12:13]
	v_or_b32_e32 v14, v14, v8
	v_cndmask_b32_e64 v12, -|v5|, v7, vcc
	v_lshlrev_b64 v[12:13], 8, v[12:13]
	v_or_b32_e32 v12, v12, v10
.LBB0_3873:
	s_lshl_b64 s[26:27], 1, s28
	s_or_b64 s[26:27], s[26:27], s[88:89]
	v_cmp_le_u64_e64 s[56:57], s[26:27], v[18:19]
	v_cmp_le_u64_e64 s[92:93], s[26:27], v[16:17]
	v_cmp_le_u64_e64 s[98:99], s[26:27], v[14:15]
	v_cmp_le_u64_e32 vcc, s[26:27], v[12:13]
	s_bcnt1_i32_b64 s51, s[56:57]
	s_bcnt1_i32_b64 s53, s[92:93]
	s_add_i32 s51, s51, s53
	s_bcnt1_i32_b64 s53, s[98:99]
	s_add_i32 s51, s51, s53
	s_bcnt1_i32_b64 s53, vcc
	s_add_i32 s51, s51, s53
	s_cmp_gt_u32 s51, 15
	s_cselect_b32 s89, s27, s89
	s_cselect_b32 s88, s26, s88
	s_cmp_lg_u32 s51, 16
	s_cselect_b64 s[26:27], -1, 0
	s_cmp_lg_u32 s28, 0
	s_cselect_b64 vcc, -1, 0
	s_and_b64 s[26:27], s[26:27], vcc
	s_add_u32 s28, s28, -1
	s_addc_u32 s29, s29, -1
	s_and_b64 vcc, exec, s[26:27]
	s_cbranch_vccnz .LBB0_3873
	v_cmp_le_u64_e32 vcc, s[88:89], v[18:19]
	v_mov_b32_e32 v19, v0
	s_nop 0
	v_and_b32_e32 v7, vcc_lo, v2
	v_and_b32_e32 v5, vcc_hi, v1
	v_bcnt_u32_b32 v7, v7, 0
	v_bcnt_u32_b32 v18, v5, v7
	v_cmp_gt_u64_e64 s[28:29], 16, v[18:19]
	s_and_b64 s[26:27], vcc, s[28:29]
	s_and_saveexec_b64 s[28:29], s[26:27]
	v_lshl_add_u32 v5, v18, 2, s94
	ds_write_b32 v5, v3
	s_or_b64 exec, exec, s[28:29]
	s_bcnt1_i32_b64 s51, vcc
	v_cmp_le_u64_e32 vcc, s[88:89], v[16:17]
	s_nop 1
	v_and_b32_e32 v7, vcc_lo, v2
	v_and_b32_e32 v5, vcc_hi, v1
	v_bcnt_u32_b32 v7, v7, 0
	v_bcnt_u32_b32 v5, v5, v7
	v_add_u32_e32 v5, s51, v5
	v_cmp_gt_u32_e64 s[28:29], 16, v5
	s_and_b64 s[26:27], vcc, s[28:29]
	s_and_saveexec_b64 s[28:29], s[26:27]
	v_lshl_add_u32 v5, v5, 2, s94
	ds_write_b32 v5, v11
	s_or_b64 exec, exec, s[28:29]
	s_bcnt1_i32_b64 s26, vcc
	v_cmp_le_u64_e32 vcc, s[88:89], v[14:15]
	s_add_i32 s51, s26, s51
	s_nop 0
	v_and_b32_e32 v7, vcc_lo, v2
	v_and_b32_e32 v5, vcc_hi, v1
	v_bcnt_u32_b32 v7, v7, 0
	v_bcnt_u32_b32 v5, v5, v7
	v_add_u32_e32 v5, s51, v5
	v_cmp_gt_u32_e64 s[28:29], 16, v5
	s_and_b64 s[26:27], vcc, s[28:29]
	s_and_saveexec_b64 s[28:29], s[26:27]
	v_lshl_add_u32 v5, v5, 2, s94
	ds_write_b32 v5, v20
	s_or_b64 exec, exec, s[28:29]
	s_bcnt1_i32_b64 s26, vcc
	v_cmp_le_u64_e32 vcc, s[88:89], v[12:13]
	s_add_i32 s51, s51, s26
	s_nop 0
	v_and_b32_e32 v7, vcc_lo, v2
	v_and_b32_e32 v5, vcc_hi, v1
	v_bcnt_u32_b32 v7, v7, 0
	v_bcnt_u32_b32 v5, v5, v7
	v_add_u32_e32 v5, s51, v5
	v_cmp_gt_u32_e64 s[28:29], 16, v5
	s_and_b64 s[26:27], vcc, s[28:29]
	s_and_saveexec_b64 s[28:29], s[26:27]
	v_lshl_add_u32 v5, v5, 2, s94
	ds_write_b32 v5, v21
	s_or_b64 exec, exec, s[28:29]
	v_lshl_add_u32 v5, v175, 2, s33
	ds_read2st64_b32 v[12:13], v5 offset1:1
	ds_read2st64_b32 v[22:23], v5 offset0:2 offset1:3
	v_mov_b32_e32 v15, v0
	s_mov_b64 s[88:89], 0
	s_mov_b64 s[28:29], 39
	s_waitcnt lgkmcnt(1)
	v_cndmask_b32_e64 v5, v12, v173, s[10:11]
	v_cndmask_b32_e64 v5, v5, v170, s[12:13]
	v_cndmask_b32_e64 v7, v13, v173, s[16:17]
	v_not_b32_e32 v9, v5
	v_cmp_gt_i32_e32 vcc, 0, v5
	v_mov_b32_e32 v13, v0
	s_nop 0
	v_cndmask_b32_e64 v14, -|v5|, v9, vcc
	v_cndmask_b32_e64 v5, v7, v170, s[14:15]
	v_not_b32_e32 v7, v5
	v_cmp_gt_i32_e32 vcc, 0, v5
	v_lshlrev_b64 v[18:19], 8, v[14:15]
	v_or_b32_e32 v18, v18, v4
	v_cndmask_b32_e64 v12, -|v5|, v7, vcc
	s_waitcnt lgkmcnt(0)
	v_cndmask_b32_e64 v5, v22, v173, s[18:19]
	v_cndmask_b32_e64 v5, v5, v170, s[20:21]
	v_not_b32_e32 v7, v5
	v_cmp_gt_i32_e32 vcc, 0, v5
	v_lshlrev_b64 v[16:17], 8, v[12:13]
	v_or_b32_e32 v16, v16, v6
	v_cndmask_b32_e64 v12, -|v5|, v7, vcc
	v_cndmask_b32_e64 v5, v23, v173, s[22:23]
	v_cndmask_b32_e64 v5, v5, v170, s[24:25]
	v_not_b32_e32 v7, v5
	v_cmp_gt_i32_e32 vcc, 0, v5
	v_lshlrev_b64 v[14:15], 8, v[12:13]
	v_or_b32_e32 v14, v14, v8
	v_cndmask_b32_e64 v12, -|v5|, v7, vcc
	v_lshlrev_b64 v[12:13], 8, v[12:13]
	v_or_b32_e32 v12, v12, v10
.LBB0_3883:
	s_lshl_b64 s[26:27], 1, s28
	s_or_b64 s[26:27], s[26:27], s[88:89]
	v_cmp_le_u64_e64 s[56:57], s[26:27], v[18:19]
	v_cmp_le_u64_e64 s[92:93], s[26:27], v[16:17]
	v_cmp_le_u64_e64 s[98:99], s[26:27], v[14:15]
	v_cmp_le_u64_e32 vcc, s[26:27], v[12:13]
	s_bcnt1_i32_b64 s51, s[56:57]
	s_bcnt1_i32_b64 s53, s[92:93]
	s_add_i32 s51, s51, s53
	s_bcnt1_i32_b64 s53, s[98:99]
	s_add_i32 s51, s51, s53
	s_bcnt1_i32_b64 s53, vcc
	s_add_i32 s51, s51, s53
	s_cmp_gt_u32 s51, 15
	s_cselect_b32 s89, s27, s89
	s_cselect_b32 s88, s26, s88
	s_cmp_lg_u32 s51, 16
	s_cselect_b64 s[26:27], -1, 0
	s_cmp_lg_u32 s28, 0
	s_cselect_b64 vcc, -1, 0
	s_and_b64 s[26:27], s[26:27], vcc
	s_add_u32 s28, s28, -1
	s_addc_u32 s29, s29, -1
	s_and_b64 vcc, exec, s[26:27]
	s_cbranch_vccnz .LBB0_3883
	v_cmp_le_u64_e32 vcc, s[88:89], v[18:19]
	v_mov_b32_e32 v19, v0
	s_nop 0
	v_and_b32_e32 v7, vcc_lo, v2
	v_and_b32_e32 v5, vcc_hi, v1
	v_bcnt_u32_b32 v7, v7, 0
	v_bcnt_u32_b32 v18, v5, v7
	v_cmp_gt_u64_e64 s[28:29], 16, v[18:19]
	s_and_b64 s[26:27], vcc, s[28:29]
	s_and_saveexec_b64 s[28:29], s[26:27]
	v_lshl_add_u32 v5, v18, 2, s45
	ds_write_b32 v5, v3
	s_or_b64 exec, exec, s[28:29]
	s_bcnt1_i32_b64 s51, vcc
	v_cmp_le_u64_e32 vcc, s[88:89], v[16:17]
	s_nop 1
	v_and_b32_e32 v7, vcc_lo, v2
	v_and_b32_e32 v5, vcc_hi, v1
	v_bcnt_u32_b32 v7, v7, 0
	v_bcnt_u32_b32 v5, v5, v7
	v_add_u32_e32 v5, s51, v5
	v_cmp_gt_u32_e64 s[28:29], 16, v5
	s_and_b64 s[26:27], vcc, s[28:29]
	s_and_saveexec_b64 s[28:29], s[26:27]
	v_lshl_add_u32 v5, v5, 2, s45
	ds_write_b32 v5, v11
	s_or_b64 exec, exec, s[28:29]
	s_bcnt1_i32_b64 s26, vcc
	v_cmp_le_u64_e32 vcc, s[88:89], v[14:15]
	s_add_i32 s51, s26, s51
	s_nop 0
	v_and_b32_e32 v7, vcc_lo, v2
	v_and_b32_e32 v5, vcc_hi, v1
	v_bcnt_u32_b32 v7, v7, 0
	v_bcnt_u32_b32 v5, v5, v7
	v_add_u32_e32 v5, s51, v5
	v_cmp_gt_u32_e64 s[28:29], 16, v5
	s_and_b64 s[26:27], vcc, s[28:29]
	s_and_saveexec_b64 s[28:29], s[26:27]
	v_lshl_add_u32 v5, v5, 2, s45
	ds_write_b32 v5, v20
	s_or_b64 exec, exec, s[28:29]
	s_bcnt1_i32_b64 s26, vcc
	v_cmp_le_u64_e32 vcc, s[88:89], v[12:13]
	s_add_i32 s51, s51, s26
	s_nop 0
	v_and_b32_e32 v7, vcc_lo, v2
	v_and_b32_e32 v5, vcc_hi, v1
	v_bcnt_u32_b32 v7, v7, 0
	v_bcnt_u32_b32 v5, v5, v7
	v_add_u32_e32 v5, s51, v5
	v_cmp_gt_u32_e64 s[28:29], 16, v5
	s_and_b64 s[26:27], vcc, s[28:29]
	s_and_saveexec_b64 s[28:29], s[26:27]
	v_lshl_add_u32 v5, v5, 2, s45
	ds_write_b32 v5, v21
	s_or_b64 exec, exec, s[28:29]
	v_lshl_add_u32 v5, v175, 2, s44
	ds_read2st64_b32 v[12:13], v5 offset1:1
	ds_read2st64_b32 v[22:23], v5 offset0:2 offset1:3
	v_mov_b32_e32 v15, v0
	s_mov_b64 s[88:89], 0
	s_mov_b64 s[28:29], 39
	s_waitcnt lgkmcnt(1)
	v_cndmask_b32_e64 v5, v12, v173, s[10:11]
	v_cndmask_b32_e64 v5, v5, v170, s[12:13]
	v_cndmask_b32_e64 v7, v13, v173, s[16:17]
	v_not_b32_e32 v9, v5
	v_cmp_gt_i32_e32 vcc, 0, v5
	v_mov_b32_e32 v13, v0
	s_nop 0
	v_cndmask_b32_e64 v14, -|v5|, v9, vcc
	v_cndmask_b32_e64 v5, v7, v170, s[14:15]
	v_not_b32_e32 v7, v5
	v_cmp_gt_i32_e32 vcc, 0, v5
	v_lshlrev_b64 v[18:19], 8, v[14:15]
	v_or_b32_e32 v18, v18, v4
	v_cndmask_b32_e64 v12, -|v5|, v7, vcc
	s_waitcnt lgkmcnt(0)
	v_cndmask_b32_e64 v5, v22, v173, s[18:19]
	v_cndmask_b32_e64 v5, v5, v170, s[20:21]
	v_not_b32_e32 v7, v5
	v_cmp_gt_i32_e32 vcc, 0, v5
	v_lshlrev_b64 v[16:17], 8, v[12:13]
	v_or_b32_e32 v16, v16, v6
	v_cndmask_b32_e64 v12, -|v5|, v7, vcc
	v_cndmask_b32_e64 v5, v23, v173, s[22:23]
	v_cndmask_b32_e64 v5, v5, v170, s[24:25]
	v_not_b32_e32 v7, v5
	v_cmp_gt_i32_e32 vcc, 0, v5
	v_lshlrev_b64 v[14:15], 8, v[12:13]
	v_or_b32_e32 v14, v14, v8
	v_cndmask_b32_e64 v12, -|v5|, v7, vcc
	v_lshlrev_b64 v[12:13], 8, v[12:13]
	v_or_b32_e32 v12, v12, v10
.LBB0_3893:
	s_lshl_b64 s[26:27], 1, s28
	s_or_b64 s[26:27], s[26:27], s[88:89]
	v_cmp_le_u64_e64 s[56:57], s[26:27], v[18:19]
	v_cmp_le_u64_e64 s[92:93], s[26:27], v[16:17]
	v_cmp_le_u64_e64 s[98:99], s[26:27], v[14:15]
	v_cmp_le_u64_e32 vcc, s[26:27], v[12:13]
	s_bcnt1_i32_b64 s51, s[56:57]
	s_bcnt1_i32_b64 s53, s[92:93]
	s_add_i32 s51, s51, s53
	s_bcnt1_i32_b64 s53, s[98:99]
	s_add_i32 s51, s51, s53
	s_bcnt1_i32_b64 s53, vcc
	s_add_i32 s51, s51, s53
	s_cmp_gt_u32 s51, 15
	s_cselect_b32 s89, s27, s89
	s_cselect_b32 s88, s26, s88
	s_cmp_lg_u32 s51, 16
	s_cselect_b64 s[26:27], -1, 0
	s_cmp_lg_u32 s28, 0
	s_cselect_b64 vcc, -1, 0
	s_and_b64 s[26:27], s[26:27], vcc
	s_add_u32 s28, s28, -1
	s_addc_u32 s29, s29, -1
	s_and_b64 vcc, exec, s[26:27]
	s_cbranch_vccnz .LBB0_3893
	v_cmp_le_u64_e32 vcc, s[88:89], v[18:19]
	v_mov_b32_e32 v19, v0
	s_nop 0
	v_and_b32_e32 v7, vcc_lo, v2
	v_and_b32_e32 v5, vcc_hi, v1
	v_bcnt_u32_b32 v7, v7, 0
	v_bcnt_u32_b32 v18, v5, v7
	v_cmp_gt_u64_e64 s[28:29], 16, v[18:19]
	s_and_b64 s[26:27], vcc, s[28:29]
	s_and_saveexec_b64 s[28:29], s[26:27]
	v_lshl_add_u32 v5, v18, 2, s47
	ds_write_b32 v5, v3
	s_or_b64 exec, exec, s[28:29]
	s_bcnt1_i32_b64 s51, vcc
	v_cmp_le_u64_e32 vcc, s[88:89], v[16:17]
	s_nop 1
	v_and_b32_e32 v7, vcc_lo, v2
	v_and_b32_e32 v5, vcc_hi, v1
	v_bcnt_u32_b32 v7, v7, 0
	v_bcnt_u32_b32 v5, v5, v7
	v_add_u32_e32 v5, s51, v5
	v_cmp_gt_u32_e64 s[28:29], 16, v5
	s_and_b64 s[26:27], vcc, s[28:29]
	s_and_saveexec_b64 s[28:29], s[26:27]
	v_lshl_add_u32 v5, v5, 2, s47
	ds_write_b32 v5, v11
	s_or_b64 exec, exec, s[28:29]
	s_bcnt1_i32_b64 s26, vcc
	v_cmp_le_u64_e32 vcc, s[88:89], v[14:15]
	s_add_i32 s51, s26, s51
	s_nop 0
	v_and_b32_e32 v7, vcc_lo, v2
	v_and_b32_e32 v5, vcc_hi, v1
	v_bcnt_u32_b32 v7, v7, 0
	v_bcnt_u32_b32 v5, v5, v7
	v_add_u32_e32 v5, s51, v5
	v_cmp_gt_u32_e64 s[28:29], 16, v5
	s_and_b64 s[26:27], vcc, s[28:29]
	s_and_saveexec_b64 s[28:29], s[26:27]
	v_lshl_add_u32 v5, v5, 2, s47
	ds_write_b32 v5, v20
	s_or_b64 exec, exec, s[28:29]
	s_bcnt1_i32_b64 s26, vcc
	v_cmp_le_u64_e32 vcc, s[88:89], v[12:13]
	s_add_i32 s51, s51, s26
	s_nop 0
	v_and_b32_e32 v7, vcc_lo, v2
	v_and_b32_e32 v5, vcc_hi, v1
	v_bcnt_u32_b32 v7, v7, 0
	v_bcnt_u32_b32 v5, v5, v7
	v_add_u32_e32 v5, s51, v5
	v_cmp_gt_u32_e64 s[28:29], 16, v5
	s_and_b64 s[26:27], vcc, s[28:29]
	s_and_saveexec_b64 s[28:29], s[26:27]
	v_lshl_add_u32 v5, v5, 2, s47
	ds_write_b32 v5, v21
	s_or_b64 exec, exec, s[28:29]
	v_lshl_add_u32 v5, v175, 2, s46
	ds_read2st64_b32 v[12:13], v5 offset1:1
	ds_read2st64_b32 v[22:23], v5 offset0:2 offset1:3
	v_mov_b32_e32 v15, v0
	s_mov_b64 s[88:89], 0
	s_mov_b64 s[28:29], 39
	s_waitcnt lgkmcnt(1)
	v_cndmask_b32_e64 v5, v12, v173, s[10:11]
	v_cndmask_b32_e64 v5, v5, v170, s[12:13]
	v_cndmask_b32_e64 v7, v13, v173, s[16:17]
	v_not_b32_e32 v9, v5
	v_cmp_gt_i32_e32 vcc, 0, v5
	v_mov_b32_e32 v13, v0
	s_nop 0
	v_cndmask_b32_e64 v14, -|v5|, v9, vcc
	v_cndmask_b32_e64 v5, v7, v170, s[14:15]
	v_not_b32_e32 v7, v5
	v_cmp_gt_i32_e32 vcc, 0, v5
	v_lshlrev_b64 v[18:19], 8, v[14:15]
	v_or_b32_e32 v18, v18, v4
	v_cndmask_b32_e64 v12, -|v5|, v7, vcc
	s_waitcnt lgkmcnt(0)
	v_cndmask_b32_e64 v5, v22, v173, s[18:19]
	v_cndmask_b32_e64 v5, v5, v170, s[20:21]
	v_not_b32_e32 v7, v5
	v_cmp_gt_i32_e32 vcc, 0, v5
	v_lshlrev_b64 v[16:17], 8, v[12:13]
	v_or_b32_e32 v16, v16, v6
	v_cndmask_b32_e64 v12, -|v5|, v7, vcc
	v_cndmask_b32_e64 v5, v23, v173, s[22:23]
	v_cndmask_b32_e64 v5, v5, v170, s[24:25]
	v_not_b32_e32 v7, v5
	v_cmp_gt_i32_e32 vcc, 0, v5
	v_lshlrev_b64 v[14:15], 8, v[12:13]
	v_or_b32_e32 v14, v14, v8
	v_cndmask_b32_e64 v12, -|v5|, v7, vcc
	v_lshlrev_b64 v[12:13], 8, v[12:13]
	v_or_b32_e32 v12, v12, v10
.LBB0_3903:
	s_lshl_b64 s[26:27], 1, s28
	s_or_b64 s[26:27], s[26:27], s[88:89]
	v_cmp_le_u64_e64 s[56:57], s[26:27], v[18:19]
	v_cmp_le_u64_e64 s[92:93], s[26:27], v[16:17]
	v_cmp_le_u64_e64 s[98:99], s[26:27], v[14:15]
	v_cmp_le_u64_e32 vcc, s[26:27], v[12:13]
	s_bcnt1_i32_b64 s51, s[56:57]
	s_bcnt1_i32_b64 s53, s[92:93]
	s_add_i32 s51, s51, s53
	s_bcnt1_i32_b64 s53, s[98:99]
	s_add_i32 s51, s51, s53
	s_bcnt1_i32_b64 s53, vcc
	s_add_i32 s51, s51, s53
	s_cmp_gt_u32 s51, 15
	s_cselect_b32 s89, s27, s89
	s_cselect_b32 s88, s26, s88
	s_cmp_lg_u32 s51, 16
	s_cselect_b64 s[26:27], -1, 0
	s_cmp_lg_u32 s28, 0
	s_cselect_b64 vcc, -1, 0
	s_and_b64 s[26:27], s[26:27], vcc
	s_add_u32 s28, s28, -1
	s_addc_u32 s29, s29, -1
	s_and_b64 vcc, exec, s[26:27]
	s_cbranch_vccnz .LBB0_3903
	v_cmp_le_u64_e32 vcc, s[88:89], v[18:19]
	v_mov_b32_e32 v19, v0
	s_nop 0
	v_and_b32_e32 v7, vcc_lo, v2
	v_and_b32_e32 v5, vcc_hi, v1
	v_bcnt_u32_b32 v7, v7, 0
	v_bcnt_u32_b32 v18, v5, v7
	v_cmp_gt_u64_e64 s[28:29], 16, v[18:19]
	s_and_b64 s[26:27], vcc, s[28:29]
	s_and_saveexec_b64 s[28:29], s[26:27]
	v_lshl_add_u32 v5, v18, 2, s63
	ds_write_b32 v5, v3
	s_or_b64 exec, exec, s[28:29]
	s_bcnt1_i32_b64 s51, vcc
	v_cmp_le_u64_e32 vcc, s[88:89], v[16:17]
	s_nop 1
	v_and_b32_e32 v7, vcc_lo, v2
	v_and_b32_e32 v5, vcc_hi, v1
	v_bcnt_u32_b32 v7, v7, 0
	v_bcnt_u32_b32 v5, v5, v7
	v_add_u32_e32 v5, s51, v5
	v_cmp_gt_u32_e64 s[28:29], 16, v5
	s_and_b64 s[26:27], vcc, s[28:29]
	s_and_saveexec_b64 s[28:29], s[26:27]
	v_lshl_add_u32 v5, v5, 2, s63
	ds_write_b32 v5, v11
	s_or_b64 exec, exec, s[28:29]
	s_bcnt1_i32_b64 s26, vcc
	v_cmp_le_u64_e32 vcc, s[88:89], v[14:15]
	s_add_i32 s51, s26, s51
	s_nop 0
	v_and_b32_e32 v7, vcc_lo, v2
	v_and_b32_e32 v5, vcc_hi, v1
	v_bcnt_u32_b32 v7, v7, 0
	v_bcnt_u32_b32 v5, v5, v7
	v_add_u32_e32 v5, s51, v5
	v_cmp_gt_u32_e64 s[28:29], 16, v5
	s_and_b64 s[26:27], vcc, s[28:29]
	s_and_saveexec_b64 s[28:29], s[26:27]
	v_lshl_add_u32 v5, v5, 2, s63
	ds_write_b32 v5, v20
	s_or_b64 exec, exec, s[28:29]
	s_bcnt1_i32_b64 s26, vcc
	v_cmp_le_u64_e32 vcc, s[88:89], v[12:13]
	s_add_i32 s51, s51, s26
	s_nop 0
	v_and_b32_e32 v7, vcc_lo, v2
	v_and_b32_e32 v5, vcc_hi, v1
	v_bcnt_u32_b32 v7, v7, 0
	v_bcnt_u32_b32 v5, v5, v7
	v_add_u32_e32 v5, s51, v5
	v_cmp_gt_u32_e64 s[28:29], 16, v5
	s_and_b64 s[26:27], vcc, s[28:29]
	s_and_saveexec_b64 s[28:29], s[26:27]
	v_lshl_add_u32 v5, v5, 2, s63
	ds_write_b32 v5, v21
	s_or_b64 exec, exec, s[28:29]
	v_lshl_add_u32 v5, v175, 2, s62
	ds_read2st64_b32 v[12:13], v5 offset1:1
	ds_read2st64_b32 v[22:23], v5 offset0:2 offset1:3
	v_mov_b32_e32 v15, v0
	s_mov_b64 s[88:89], 0
	s_mov_b64 s[28:29], 39
	s_waitcnt lgkmcnt(1)
	v_cndmask_b32_e64 v5, v12, v173, s[10:11]
	v_cndmask_b32_e64 v5, v5, v170, s[12:13]
	v_cndmask_b32_e64 v7, v13, v173, s[16:17]
	v_not_b32_e32 v9, v5
	v_cmp_gt_i32_e32 vcc, 0, v5
	v_mov_b32_e32 v13, v0
	s_nop 0
	v_cndmask_b32_e64 v14, -|v5|, v9, vcc
	v_cndmask_b32_e64 v5, v7, v170, s[14:15]
	v_not_b32_e32 v7, v5
	v_cmp_gt_i32_e32 vcc, 0, v5
	v_lshlrev_b64 v[18:19], 8, v[14:15]
	v_or_b32_e32 v18, v18, v4
	v_cndmask_b32_e64 v12, -|v5|, v7, vcc
	s_waitcnt lgkmcnt(0)
	v_cndmask_b32_e64 v5, v22, v173, s[18:19]
	v_cndmask_b32_e64 v5, v5, v170, s[20:21]
	v_not_b32_e32 v7, v5
	v_cmp_gt_i32_e32 vcc, 0, v5
	v_lshlrev_b64 v[16:17], 8, v[12:13]
	v_or_b32_e32 v16, v16, v6
	v_cndmask_b32_e64 v12, -|v5|, v7, vcc
	v_cndmask_b32_e64 v5, v23, v173, s[22:23]
	v_cndmask_b32_e64 v5, v5, v170, s[24:25]
	v_not_b32_e32 v7, v5
	v_cmp_gt_i32_e32 vcc, 0, v5
	v_lshlrev_b64 v[14:15], 8, v[12:13]
	v_or_b32_e32 v14, v14, v8
	v_cndmask_b32_e64 v12, -|v5|, v7, vcc
	v_lshlrev_b64 v[12:13], 8, v[12:13]
	v_or_b32_e32 v12, v12, v10
.LBB0_3913:
	s_lshl_b64 s[26:27], 1, s28
	s_or_b64 s[26:27], s[26:27], s[88:89]
	v_cmp_le_u64_e64 s[56:57], s[26:27], v[18:19]
	v_cmp_le_u64_e64 s[92:93], s[26:27], v[16:17]
	v_cmp_le_u64_e64 s[98:99], s[26:27], v[14:15]
	v_cmp_le_u64_e32 vcc, s[26:27], v[12:13]
	s_bcnt1_i32_b64 s51, s[56:57]
	s_bcnt1_i32_b64 s53, s[92:93]
	s_add_i32 s51, s51, s53
	s_bcnt1_i32_b64 s53, s[98:99]
	s_add_i32 s51, s51, s53
	s_bcnt1_i32_b64 s53, vcc
	s_add_i32 s51, s51, s53
	s_cmp_gt_u32 s51, 15
	s_cselect_b32 s89, s27, s89
	s_cselect_b32 s88, s26, s88
	s_cmp_lg_u32 s51, 16
	s_cselect_b64 s[26:27], -1, 0
	s_cmp_lg_u32 s28, 0
	s_cselect_b64 vcc, -1, 0
	s_and_b64 s[26:27], s[26:27], vcc
	s_add_u32 s28, s28, -1
	s_addc_u32 s29, s29, -1
	s_and_b64 vcc, exec, s[26:27]
	s_cbranch_vccnz .LBB0_3913
	v_cmp_le_u64_e32 vcc, s[88:89], v[18:19]
	v_mov_b32_e32 v19, v0
	s_nop 0
	v_and_b32_e32 v7, vcc_lo, v2
	v_and_b32_e32 v5, vcc_hi, v1
	v_bcnt_u32_b32 v7, v7, 0
	v_bcnt_u32_b32 v18, v5, v7
	v_cmp_gt_u64_e64 s[28:29], 16, v[18:19]
	s_and_b64 s[26:27], vcc, s[28:29]
	s_and_saveexec_b64 s[28:29], s[26:27]
	v_lshl_add_u32 v5, v18, 2, s59
	ds_write_b32 v5, v3
	s_or_b64 exec, exec, s[28:29]
	s_bcnt1_i32_b64 s51, vcc
	v_cmp_le_u64_e32 vcc, s[88:89], v[16:17]
	s_nop 1
	v_and_b32_e32 v7, vcc_lo, v2
	v_and_b32_e32 v5, vcc_hi, v1
	v_bcnt_u32_b32 v7, v7, 0
	v_bcnt_u32_b32 v5, v5, v7
	v_add_u32_e32 v5, s51, v5
	v_cmp_gt_u32_e64 s[28:29], 16, v5
	s_and_b64 s[26:27], vcc, s[28:29]
	s_and_saveexec_b64 s[28:29], s[26:27]
	v_lshl_add_u32 v5, v5, 2, s59
	ds_write_b32 v5, v11
	s_or_b64 exec, exec, s[28:29]
	s_bcnt1_i32_b64 s26, vcc
	v_cmp_le_u64_e32 vcc, s[88:89], v[14:15]
	s_add_i32 s51, s26, s51
	s_nop 0
	v_and_b32_e32 v7, vcc_lo, v2
	v_and_b32_e32 v5, vcc_hi, v1
	v_bcnt_u32_b32 v7, v7, 0
	v_bcnt_u32_b32 v5, v5, v7
	v_add_u32_e32 v5, s51, v5
	v_cmp_gt_u32_e64 s[28:29], 16, v5
	s_and_b64 s[26:27], vcc, s[28:29]
	s_and_saveexec_b64 s[28:29], s[26:27]
	v_lshl_add_u32 v5, v5, 2, s59
	ds_write_b32 v5, v20
	s_or_b64 exec, exec, s[28:29]
	s_bcnt1_i32_b64 s26, vcc
	v_cmp_le_u64_e32 vcc, s[88:89], v[12:13]
	s_add_i32 s51, s51, s26
	s_nop 0
	v_and_b32_e32 v7, vcc_lo, v2
	v_and_b32_e32 v5, vcc_hi, v1
	v_bcnt_u32_b32 v7, v7, 0
	v_bcnt_u32_b32 v5, v5, v7
	v_add_u32_e32 v5, s51, v5
	v_cmp_gt_u32_e64 s[28:29], 16, v5
	s_and_b64 s[26:27], vcc, s[28:29]
	s_and_saveexec_b64 s[28:29], s[26:27]
	v_lshl_add_u32 v5, v5, 2, s59
	ds_write_b32 v5, v21
	s_or_b64 exec, exec, s[28:29]
	v_lshl_add_u32 v5, v175, 2, s58
	ds_read2st64_b32 v[12:13], v5 offset1:1
	ds_read2st64_b32 v[16:17], v5 offset0:2 offset1:3
	v_mov_b32_e32 v15, v0
	s_waitcnt lgkmcnt(1)
	v_cndmask_b32_e64 v5, v12, v173, s[10:11]
	v_cndmask_b32_e64 v5, v5, v170, s[12:13]
	v_not_b32_e32 v9, v5
	v_cmp_gt_i32_e32 vcc, 0, v5
	v_cndmask_b32_e64 v7, v13, v173, s[16:17]
	s_mov_b64 s[12:13], 0
	v_cndmask_b32_e64 v14, -|v5|, v9, vcc
	v_lshlrev_b64 v[14:15], 8, v[14:15]
	v_or_b32_e32 v14, v14, v4
	v_cndmask_b32_e64 v4, v7, v170, s[14:15]
	v_not_b32_e32 v5, v4
	v_cmp_gt_i32_e32 vcc, 0, v4
	s_mov_b64 s[10:11], 39
	s_nop 0
	v_cndmask_b32_e64 v4, -|v4|, v5, vcc
	v_mov_b32_e32 v5, v0
	v_lshlrev_b64 v[12:13], 8, v[4:5]
	s_waitcnt lgkmcnt(0)
	v_cndmask_b32_e64 v4, v16, v173, s[18:19]
	v_cndmask_b32_e64 v4, v4, v170, s[20:21]
	v_not_b32_e32 v5, v4
	v_cmp_gt_i32_e32 vcc, 0, v4
	v_or_b32_e32 v12, v12, v6
	s_nop 0
	v_cndmask_b32_e64 v4, -|v4|, v5, vcc
	v_mov_b32_e32 v5, v0
	v_lshlrev_b64 v[6:7], 8, v[4:5]
	v_cndmask_b32_e64 v4, v17, v173, s[22:23]
	v_cndmask_b32_e64 v4, v4, v170, s[24:25]
	v_not_b32_e32 v5, v4
	v_cmp_gt_i32_e32 vcc, 0, v4
	v_or_b32_e32 v6, v6, v8
	s_nop 0
	v_cndmask_b32_e64 v4, -|v4|, v5, vcc
	v_mov_b32_e32 v5, v0
	v_lshlrev_b64 v[4:5], 8, v[4:5]
	v_or_b32_e32 v4, v4, v10
.LBB0_3923:
	s_lshl_b64 s[14:15], 1, s10
	s_or_b64 s[14:15], s[14:15], s[12:13]
	v_cmp_le_u64_e64 s[56:57], s[14:15], v[14:15]
	v_cmp_le_u64_e64 s[92:93], s[14:15], v[12:13]
	v_cmp_le_u64_e64 s[98:99], s[14:15], v[6:7]
	v_cmp_le_u64_e32 vcc, s[14:15], v[4:5]
	s_bcnt1_i32_b64 s16, s[56:57]
	s_bcnt1_i32_b64 s17, s[92:93]
	s_add_i32 s16, s16, s17
	s_bcnt1_i32_b64 s17, s[98:99]
	s_add_i32 s16, s16, s17
	s_bcnt1_i32_b64 s17, vcc
	s_add_i32 s16, s16, s17
	s_cmp_gt_u32 s16, 15
	s_cselect_b32 s13, s15, s13
	s_cselect_b32 s12, s14, s12
	s_cmp_lg_u32 s16, 16
	s_cselect_b64 s[14:15], -1, 0
	s_cmp_lg_u32 s10, 0
	s_cselect_b64 s[16:17], -1, 0
	s_and_b64 s[14:15], s[14:15], s[16:17]
	s_add_u32 s10, s10, -1
	s_addc_u32 s11, s11, -1
	s_and_b64 vcc, exec, s[14:15]
	s_cbranch_vccnz .LBB0_3923
	v_cmp_le_u64_e32 vcc, s[12:13], v[14:15]
	s_nop 1
	v_and_b32_e32 v9, vcc_lo, v2
	v_and_b32_e32 v8, vcc_hi, v1
	v_bcnt_u32_b32 v9, v9, 0
	v_bcnt_u32_b32 v8, v8, v9
	v_mov_b32_e32 v9, v0
	v_cmp_gt_u64_e64 s[10:11], 16, v[8:9]
	s_and_b64 s[14:15], vcc, s[10:11]
	s_and_saveexec_b64 s[10:11], s[14:15]
	v_lshl_add_u32 v8, v8, 2, s61
	ds_write_b32 v8, v3
	s_or_b64 exec, exec, s[10:11]
	s_bcnt1_i32_b64 s14, vcc
	v_cmp_le_u64_e32 vcc, s[12:13], v[12:13]
	s_nop 1
	v_and_b32_e32 v8, vcc_lo, v2
	v_and_b32_e32 v3, vcc_hi, v1
	v_bcnt_u32_b32 v8, v8, 0
	v_bcnt_u32_b32 v3, v3, v8
	v_add_u32_e32 v3, s14, v3
	v_cmp_gt_u32_e64 s[10:11], 16, v3
	s_and_b64 s[16:17], vcc, s[10:11]
	s_and_saveexec_b64 s[10:11], s[16:17]
	v_lshl_add_u32 v3, v3, 2, s61
	ds_write_b32 v3, v11
	s_or_b64 exec, exec, s[10:11]
	s_bcnt1_i32_b64 s10, vcc
	v_cmp_le_u64_e32 vcc, s[12:13], v[6:7]
	s_add_i32 s14, s10, s14
	s_nop 0
	v_and_b32_e32 v6, vcc_lo, v2
	v_and_b32_e32 v3, vcc_hi, v1
	v_bcnt_u32_b32 v6, v6, 0
	v_bcnt_u32_b32 v3, v3, v6
	v_add_u32_e32 v3, s14, v3
	v_cmp_gt_u32_e64 s[10:11], 16, v3
	s_and_b64 s[16:17], vcc, s[10:11]
	s_and_saveexec_b64 s[10:11], s[16:17]
	v_lshl_add_u32 v3, v3, 2, s61
	ds_write_b32 v3, v20
	s_or_b64 exec, exec, s[10:11]
	s_bcnt1_i32_b64 s10, vcc
	v_cmp_le_u64_e32 vcc, s[12:13], v[4:5]
	s_add_i32 s14, s14, s10
	s_nop 0
	v_and_b32_e32 v2, vcc_lo, v2
	v_and_b32_e32 v1, vcc_hi, v1
	v_bcnt_u32_b32 v2, v2, 0
	v_bcnt_u32_b32 v1, v1, v2
	v_add_u32_e32 v1, s14, v1
	v_cmp_gt_u32_e64 s[10:11], 16, v1
	s_and_b64 s[12:13], vcc, s[10:11]
	s_and_saveexec_b64 s[10:11], s[12:13]
	v_lshl_add_u32 v1, v1, 2, s61
	ds_write_b32 v1, v21
	s_or_b64 exec, exec, s[10:11]
	v_cmp_gt_i32_e32 vcc, s6, v49
	v_mov_b32_e32 v1, s81
	v_mov_b32_e32 v2, s79
	v_cndmask_b32_e32 v3, v1, v2, vcc
	v_mov_b32_e32 v1, s80
	v_mov_b32_e32 v2, s78
	v_cndmask_b32_e32 v2, v1, v2, vcc
	v_and_b32_e32 v4, 0xff0, v124
	v_mov_b32_e32 v5, v0
	v_lshl_add_u64 v[6:7], v[2:3], 0, v[4:5]
	v_cndmask_b32_e64 v1, v174, 0, vcc
	v_mov_b32_e32 v2, s49
	s_movk_i32 s10, 0xfe
	v_add3_u32 v1, s6, v1, v4
	v_sub_u32_e64 v8, s10, v2 clamp
	global_load_dwordx4 v[2:5], v[6:7], off
	s_lshl_b32 s54, s48, 12
	s_mov_b32 s87, s55
	s_lshl_b64 s[12:13], s[86:87], 11
	s_add_u32 s10, s38, s12
	s_addc_u32 s11, s39, s13
	v_lshlrev_b32_e32 v10, 12, v8
	v_mov_b32_e32 v11, v0
	v_lshl_add_u64 v[10:11], v[6:7], 0, v[10:11]
	global_load_dwordx4 v[10:13], v[10:11], off
	v_lshl_add_u64 v[14:15], v[6:7], 0, s[54:55]
	global_load_dwordx4 v[14:17], v[14:15], off
	v_mov_b32_e32 v7, v0
	s_waitcnt vmcnt(2)
	ds_write_b128 v1, v[2:5]
	s_waitcnt vmcnt(1)
	ds_write_b128 v1, v[10:13] offset:8192
	s_waitcnt vmcnt(0)
	ds_write_b128 v1, v[14:17] offset:16384
	v_and_b32_e32 v4, 48, v49
	v_lshlrev_b32_e32 v2, 1, v121
	v_mov_b32_e32 v3, v0
	v_lshl_add_u64 v[2:3], s[10:11], 0, v[2:3]
	v_lshlrev_b32_e32 v6, 1, v4
	v_lshl_add_u64 v[6:7], v[2:3], 0, v[6:7]
	v_mov_b32_e32 v2, v0
	v_mov_b32_e32 v3, v0
	v_mov_b32_e32 v1, v0
	v_mov_b64_e32 v[72:73], v[2:3]
	v_cmp_gt_u32_e64 s[10:11], 4, v122
	v_mov_b64_e32 v[70:71], v[0:1]
	s_waitcnt lgkmcnt(0)
	s_barrier
	v_and_b32_e32 v1, 63, v160
	v_lshrrev_b32_e32 v203, 6, v160
	v_and_b32_e32 v201, 15, v1
	v_lshrrev_b32_e32 v187, 4, v1
	v_readfirstlane_b32 s22, v203
	v_and_b32_e32 v165, 3, v201
	v_lshrrev_b32_e32 v251, 2, v201
	v_mov_b32_e32 v193, 0
	v_lshlrev_b32_e32 v192, 4, v1
	v_lshl_add_u64 v[166:167], s[78:79], 0, v[192:193]
	v_lshl_add_u64 v[190:191], s[80:81], 0, v[192:193]
	v_add_u32_e32 v188, 0x100, v192
	v_mov_b32_e32 v199, 0xf149f2ca
	s_lshl_b32 s23, s22, 9
	s_add_i32 s23, s23, 0x20900
	v_lshl_add_u32 v203, v1, 2, s23
	ds_read_b32 v252, v203
	ds_read_b32 v253, v203 offset:256
	s_lshl_b32 s23, s22, 10
	s_add_i32 s23, s23, 0x10900
	v_mov_b32_e32 v244, 0
	v_mov_b32_e32 v245, 0
	v_mov_b32_e32 v246, 0
	v_mov_b32_e32 v247, 0
	v_lshl_add_u32 v250, v1, 4, s23
	ds_write_b128 v250, v[244:247]
	v_lshrrev_b32_e32 v248, 4, v1
	v_lshlrev_b32_e64 v249, v248, 1
	v_lshlrev_b32_e32 v250, 4, v249
	s_waitcnt lgkmcnt(0)
	v_cmp_le_i32_e32 vcc, 0, v252
	v_lshl_add_u32 v203, v252, 2, s23
	s_and_saveexec_b64 s[12:13], vcc
	ds_or_b32 v203, v249
	s_mov_b64 exec, s[12:13]
	v_cmp_le_i32_e32 vcc, 0, v253
	v_lshl_add_u32 v203, v253, 2, s23
	s_and_saveexec_b64 s[12:13], vcc
	ds_or_b32 v203, v250
	s_mov_b64 exec, s[12:13]
	v_lshl_add_u32 v203, v1, 2, s23
	s_waitcnt lgkmcnt(0)
	ds_read_b32 v244, v203
	ds_read_b32 v245, v203 offset:256
	ds_read_b32 v246, v203 offset:512
	ds_read_b32 v247, v203 offset:768
	s_lshl_b32 s23, s22, 12
	s_add_i32 s23, s23, 0x8900
	v_lshl_add_u32 v207, v165, 2, v251
	v_lshl_add_u32 v207, v207, 7, s23
	v_lshl_add_u32 v207, v187, 3, v207
	s_lshl_b32 s21, s22, 3
	s_add_i32 s20, s48, -1
	s_lshl_b32 s54, s48, 6
	s_add_i32 s54, s54, s21
	s_and_b32 s101, s65, 3
	s_lshl_b32 s12, s54, 11
	s_lshl_b32 s23, s101, 9
	s_add_i32 s12, s12, s23
	s_add_u32 s12, s38, s12
	s_addc_u32 s13, s39, 0
	v_lshlrev_b32_e32 v192, 7, v251
	v_lshl_or_b32 v192, v187, 5, v192
	v_lshl_or_b32 v192, v165, 11, v192
	v_lshl_add_u64 v[192:193], s[12:13], 0, v[192:193]
	global_load_dwordx4 v[212:215], v[192:193], off
	global_load_dwordx4 v[216:219], v[192:193], off offset:16
	v_add_co_u32_e32 v192, vcc, 0x2000, v192
	s_nop 1
	v_addc_co_u32_e32 v193, vcc, 0, v193, vcc
	global_load_dwordx4 v[220:223], v[192:193], off
	global_load_dwordx4 v[224:227], v[192:193], off offset:16
	s_mul_i32 s12, s54, 0xc0
	s_lshl_b32 s23, s101, 4
	s_add_i32 s12, s12, s23
	s_add_i32 s12, s12, 0xf400040
	s_add_u32 s12, s38, s12
	s_addc_u32 s13, s39, 0
	v_mul_u32_u24_e32 v248, 0xc0, v165
	v_mov_b32_e32 v249, 0
	v_lshl_add_u32 v248, v251, 2, v248
	v_lshl_add_u64 v[248:249], s[12:13], 0, v[248:249]
	global_load_dword v208, v[248:249], off
	global_load_dword v148, v[248:249], off offset:768
	v_lshlrev_b32_e32 v187, 4, v187
	v_lshl_add_u32 v187, v251, 6, v187
	v_lshl_add_u32 v187, v165, 2, v187
	s_mov_b32 s13, 0
	s_waitcnt lgkmcnt(0)
	v_lshl_or_b32 v164, v245, 8, v244
	v_lshl_or_b32 v164, v246, 16, v164
	v_lshl_or_b32 v164, v247, 24, v164
	v_and_b32_e32 v203, 0xff, v164
	v_cmp_ne_u32_e64 s[98:99], 0, v203
	s_mov_b32 s100, 0
	v_mov_b32_e32 v158, v199
	v_mov_b32_e32 v204, 0
	v_mov_b32_e32 v159, v199
	v_mov_b32_e32 v205, 0
	v_mov_b32_e32 v162, v199
	v_mov_b32_e32 v252, 0
	v_mov_b32_e32 v163, v199
	v_mov_b32_e32 v253, 0
	v_mov_b32_e32 v102, 0
	v_mov_b32_e32 v103, 0
	v_mov_b32_e32 v104, 0
	v_mov_b32_e32 v105, 0
	v_mov_b32_e32 v106, 0
	v_mov_b32_e32 v107, 0
	v_mov_b32_e32 v108, 0
	v_mov_b32_e32 v109, 0
	v_mov_b32_e32 v110, 0
	v_mov_b32_e32 v111, 0
	v_mov_b32_e32 v112, 0
	v_mov_b32_e32 v113, 0
	v_mov_b32_e32 v114, 0
	v_mov_b32_e32 v115, 0
	v_mov_b32_e32 v116, 0
	v_mov_b32_e32 v117, 0
	v_mov_b32_e32 v197, v199
	v_mov_b32_e32 v206, 0
	v_mov_b32_e32 v198, v199
	v_mov_b32_e32 v1, 0
	v_mov_b32_e32 v200, v199
	v_mov_b32_e32 v133, 0
	v_mov_b32_e32 v202, v199
	v_mov_b32_e32 v209, 0
	v_mov_b32_e32 v118, 0
	v_mov_b32_e32 v119, 0
	v_mov_b32_e32 v120, 0
	v_mov_b32_e32 v121, 0
	v_mov_b32_e32 v122, 0
	v_mov_b32_e32 v123, 0
	v_mov_b32_e32 v124, 0
	v_mov_b32_e32 v125, 0
	v_mov_b32_e32 v136, 0
	v_mov_b32_e32 v137, 0
	v_mov_b32_e32 v138, 0
	v_mov_b32_e32 v139, 0
	v_mov_b32_e32 v140, 0
	v_mov_b32_e32 v141, 0
	v_mov_b32_e32 v142, 0
	v_mov_b32_e32 v143, 0
